# attention online softmax: lazy reference maximum (reference moves and o/l are rescaled only when a row max exceeds it by > 2^8), diff + DSA
# speedup vs baseline: 1.0102x; 1.0039x over previous
; __device__ __forceinline__ void dsa_attn_item(CParams& p, LAS unsigned char* lds, int b, int qb, int tid_in, int wave) {
;     ...
;                 float mx = -INFINITY;
; #pragma unroll
;                 for (int i = 0; i < 16; ++i) { const int ko = (i & 3) + 8 * (i >> 2) + 4 * hh; const int dist = qp - (k0 + 32 * sub + ko);
;                     float bias = bfar; if (!far) bias = bdh[dist < 0 ? 0 : (dist < 128 ? dist : 128)];
;                     const float v = ((mw >> ko) & 1u) ? sc[i] + bias : -INFINITY; sc[i] = v; mx = fmaxf(mx, v); }
;                 mx = fmaxf(mx, __shfl_xor(mx, 32));
;                 const float m_new = fmaxf(m_run, mx);
;                 const float msafe = (m_new == -INFINITY) ? 0.f : m_new;
;                 const float alpha = __builtin_amdgcn_exp2f(m_run - msafe);
;                 const bool resc = __ballot(m_new > m_run) != 0ull;
;                 float ls = 0.f;
; #pragma unroll
;                 for (int i = 0; i < 16; ++i) { const float e = __builtin_amdgcn_exp2f(sc[i] - msafe); sc[i] = e; ls += e; }
;                 ls += __shfl_xor(ls, 32);
;                 l_run = l_run * alpha + ls; m_run = m_new;
;                 if (resc) {
; #pragma unroll
;                     for (int d = 0; d < 4; ++d)
; #pragma unroll
;                         for (int i = 0; i < 16; ++i) o[d][i] *= alpha;
;                 }
.LdsaA_s0_msk:
	v_bfe_i32 v80, v214, 0, 1
	v_bfi_b32 v236, v80, v236, v225
	v_bfe_i32 v81, v214, 1, 1
	v_bfi_b32 v237, v81, v237, v225
	v_bfe_i32 v82, v214, 2, 1
	v_bfi_b32 v238, v82, v238, v225
	v_bfe_i32 v83, v214, 3, 1
	v_bfi_b32 v239, v83, v239, v225
	v_bfe_i32 v80, v214, 8, 1
	v_bfi_b32 v240, v80, v240, v225
	v_bfe_i32 v81, v214, 9, 1
	v_bfi_b32 v241, v81, v241, v225
	v_bfe_i32 v82, v214, 10, 1
	v_bfi_b32 v242, v82, v242, v225
	v_bfe_i32 v83, v214, 11, 1
	v_bfi_b32 v243, v83, v243, v225
	v_bfe_i32 v80, v214, 16, 1
	v_bfi_b32 v244, v80, v244, v225
	v_bfe_i32 v81, v214, 17, 1
	v_bfi_b32 v245, v81, v245, v225
	v_bfe_i32 v82, v214, 18, 1
	v_bfi_b32 v246, v82, v246, v225
	v_bfe_i32 v83, v214, 19, 1
	v_bfi_b32 v247, v83, v247, v225
	v_bfe_i32 v80, v214, 24, 1
	v_bfi_b32 v248, v80, v248, v225
	v_bfe_i32 v81, v214, 25, 1
	v_bfi_b32 v249, v81, v249, v225
	v_bfe_i32 v82, v214, 26, 1
	v_bfi_b32 v250, v82, v250, v225
	v_bfe_i32 v83, v214, 27, 1
	v_bfi_b32 v251, v83, v251, v225
	v_max3_f32 v84, v236, v237, v238
	v_max3_f32 v84, v84, v239, v240
	v_max3_f32 v84, v84, v241, v242
	v_max3_f32 v84, v84, v243, v244
	v_max3_f32 v84, v84, v245, v246
	v_max3_f32 v84, v84, v247, v248
	v_max3_f32 v84, v84, v249, v250
	v_max_f32_e32 v84, v84, v251
	s_waitcnt lgkmcnt(0)
	v_add_f32_e32 v84, v84, v200
	ds_bpermute_b32 v215, v185, v84
	s_waitcnt lgkmcnt(0)
	v_max3_f32 v85, v201, v84, v215
	v_add_f32_e32 v91, 0x41000000, v201
	v_cmp_gt_f32_e32 vcc, v85, v91
	s_cbranch_vccz .LdsaA_s0_keep
	v_cmp_neq_f32_e32 vcc, s78, v85
	s_nop 1
	v_cndmask_b32_e32 v86, 0, v85, vcc
	v_sub_f32_e32 v88, v201, v86
	v_exp_f32_e32 v88, v88
	v_mov_b32_e32 v201, v85
	s_nop 0
	v_mul_f32_e32 v198, v198, v88
	v_pk_mul_f32 v[64:65], v[64:65], v[88:89] op_sel_hi:[1,0]
	v_pk_mul_f32 v[66:67], v[66:67], v[88:89] op_sel_hi:[1,0]
	v_pk_mul_f32 v[68:69], v[68:69], v[88:89] op_sel_hi:[1,0]
	v_pk_mul_f32 v[70:71], v[70:71], v[88:89] op_sel_hi:[1,0]
	v_pk_mul_f32 v[72:73], v[72:73], v[88:89] op_sel_hi:[1,0]
	v_pk_mul_f32 v[74:75], v[74:75], v[88:89] op_sel_hi:[1,0]
	v_pk_mul_f32 v[76:77], v[76:77], v[88:89] op_sel_hi:[1,0]
	v_pk_mul_f32 v[78:79], v[78:79], v[88:89] op_sel_hi:[1,0]
	v_pk_mul_f32 v[48:49], v[48:49], v[88:89] op_sel_hi:[1,0]
	v_pk_mul_f32 v[50:51], v[50:51], v[88:89] op_sel_hi:[1,0]
	v_pk_mul_f32 v[52:53], v[52:53], v[88:89] op_sel_hi:[1,0]
	v_pk_mul_f32 v[54:55], v[54:55], v[88:89] op_sel_hi:[1,0]
	v_pk_mul_f32 v[56:57], v[56:57], v[88:89] op_sel_hi:[1,0]
	v_pk_mul_f32 v[58:59], v[58:59], v[88:89] op_sel_hi:[1,0]
	v_pk_mul_f32 v[60:61], v[60:61], v[88:89] op_sel_hi:[1,0]
	v_pk_mul_f32 v[62:63], v[62:63], v[88:89] op_sel_hi:[1,0]
	v_pk_mul_f32 v[32:33], v[32:33], v[88:89] op_sel_hi:[1,0]
	v_pk_mul_f32 v[34:35], v[34:35], v[88:89] op_sel_hi:[1,0]
	v_pk_mul_f32 v[36:37], v[36:37], v[88:89] op_sel_hi:[1,0]
	v_pk_mul_f32 v[38:39], v[38:39], v[88:89] op_sel_hi:[1,0]
	v_pk_mul_f32 v[40:41], v[40:41], v[88:89] op_sel_hi:[1,0]
	v_pk_mul_f32 v[42:43], v[42:43], v[88:89] op_sel_hi:[1,0]
	v_pk_mul_f32 v[44:45], v[44:45], v[88:89] op_sel_hi:[1,0]
	v_pk_mul_f32 v[46:47], v[46:47], v[88:89] op_sel_hi:[1,0]
	v_pk_mul_f32 v[16:17], v[16:17], v[88:89] op_sel_hi:[1,0]
	v_pk_mul_f32 v[18:19], v[18:19], v[88:89] op_sel_hi:[1,0]
	v_pk_mul_f32 v[20:21], v[20:21], v[88:89] op_sel_hi:[1,0]
	v_pk_mul_f32 v[22:23], v[22:23], v[88:89] op_sel_hi:[1,0]
	v_pk_mul_f32 v[24:25], v[24:25], v[88:89] op_sel_hi:[1,0]
	v_pk_mul_f32 v[26:27], v[26:27], v[88:89] op_sel_hi:[1,0]
	v_pk_mul_f32 v[28:29], v[28:29], v[88:89] op_sel_hi:[1,0]
	v_pk_mul_f32 v[30:31], v[30:31], v[88:89] op_sel_hi:[1,0]
.LdsaA_s0_keep:
	v_cmp_neq_f32_e32 vcc, s78, v201
	s_nop 1
	v_cndmask_b32_e32 v86, 0, v201, vcc
	v_sub_f32_e32 v90, v86, v200
	v_pk_add_f32 v[236:237], v[236:237], v[90:91] op_sel_hi:[1,0] neg_lo:[0,1] neg_hi:[0,1]
	v_pk_add_f32 v[238:239], v[238:239], v[90:91] op_sel_hi:[1,0] neg_lo:[0,1] neg_hi:[0,1]
	v_pk_add_f32 v[240:241], v[240:241], v[90:91] op_sel_hi:[1,0] neg_lo:[0,1] neg_hi:[0,1]
	v_pk_add_f32 v[242:243], v[242:243], v[90:91] op_sel_hi:[1,0] neg_lo:[0,1] neg_hi:[0,1]
	v_pk_add_f32 v[244:245], v[244:245], v[90:91] op_sel_hi:[1,0] neg_lo:[0,1] neg_hi:[0,1]
	v_pk_add_f32 v[246:247], v[246:247], v[90:91] op_sel_hi:[1,0] neg_lo:[0,1] neg_hi:[0,1]
	v_pk_add_f32 v[248:249], v[248:249], v[90:91] op_sel_hi:[1,0] neg_lo:[0,1] neg_hi:[0,1]
	v_pk_add_f32 v[250:251], v[250:251], v[90:91] op_sel_hi:[1,0] neg_lo:[0,1] neg_hi:[0,1]
	v_exp_f32_e32 v236, v236
	v_exp_f32_e32 v237, v237
	v_exp_f32_e32 v238, v238
	v_exp_f32_e32 v239, v239
	v_exp_f32_e32 v240, v240
	v_exp_f32_e32 v241, v241
	v_exp_f32_e32 v242, v242
	v_exp_f32_e32 v243, v243
	v_exp_f32_e32 v244, v244
	v_exp_f32_e32 v245, v245
	v_exp_f32_e32 v246, v246
	v_exp_f32_e32 v247, v247
	v_exp_f32_e32 v248, v248
	v_exp_f32_e32 v249, v249
	v_exp_f32_e32 v250, v250
	v_exp_f32_e32 v251, v251
	v_pk_add_f32 v[92:93], v[236:237], v[238:239]
	v_pk_add_f32 v[92:93], v[92:93], v[240:241]
	v_pk_add_f32 v[92:93], v[92:93], v[242:243]
	v_pk_add_f32 v[92:93], v[92:93], v[244:245]
	v_pk_add_f32 v[92:93], v[92:93], v[246:247]
	v_pk_add_f32 v[92:93], v[92:93], v[248:249]
	v_pk_add_f32 v[92:93], v[92:93], v[250:251]
	s_nop 0
	v_add_f32_e32 v92, v92, v93
	ds_bpermute_b32 v215, v185, v92
	v_cvt_pk_f16_f32 v232, v236, v237
	v_cvt_pk_f16_f32 v233, v238, v239
	v_cvt_pk_f16_f32 v234, v240, v241
	v_cvt_pk_f16_f32 v235, v242, v243
	v_cvt_pk_f16_f32 v228, v244, v245
	v_cvt_pk_f16_f32 v229, v246, v247
	v_cvt_pk_f16_f32 v230, v248, v249
	v_cvt_pk_f16_f32 v231, v250, v251
	s_waitcnt lgkmcnt(0)
	v_add_f32_e32 v92, v92, v215
	v_add_f32_e32 v198, v198, v92
	ds_read_b128 v[236:239], v199 offset:34848
	ds_read_b128 v[240:243], v199 offset:39424
	ds_read_b128 v[244:247], v199 offset:44128
	ds_read_b128 v[248:251], v199 offset:48704
	ds_read_b128 v[80:83], v199 offset:34816
	ds_read_b128 v[84:87], v199 offset:39456
	ds_read_b128 v[88:91], v199 offset:44096
	ds_read_b128 v[92:95], v199 offset:48736
	s_waitcnt lgkmcnt(4)
	v_mfma_f32_32x32x16_f16 v[64:79], v[236:239], v[228:231], v[64:79]
	v_mfma_f32_32x32x16_f16 v[48:63], v[240:243], v[228:231], v[48:63]
	v_mfma_f32_32x32x16_f16 v[32:47], v[244:247], v[228:231], v[32:47]
	v_mfma_f32_32x32x16_f16 v[16:31], v[248:251], v[228:231], v[16:31]
	s_waitcnt lgkmcnt(0)
	v_mfma_f32_32x32x16_f16 v[64:79], v[80:83], v[232:235], v[64:79]
	v_mfma_f32_32x32x16_f16 v[48:63], v[84:87], v[232:235], v[48:63]
	v_mfma_f32_32x32x16_f16 v[32:47], v[88:91], v[232:235], v[32:47]
	v_mfma_f32_32x32x16_f16 v[16:31], v[92:95], v[232:235], v[16:31]

; __device__ __forceinline__ void dsa_attn_item(CParams& p, LAS unsigned char* lds, int b, int qb, int tid_in, int wave) {
;     ...
;                 float mx = -INFINITY;
; #pragma unroll
;                 for (int i = 0; i < 16; ++i) { const int ko = (i & 3) + 8 * (i >> 2) + 4 * hh; const int dist = qp - (k0 + 32 * sub + ko);
;                     float bias = bfar; if (!far) bias = bdh[dist < 0 ? 0 : (dist < 128 ? dist : 128)];
;                     const float v = ((mw >> ko) & 1u) ? sc[i] + bias : -INFINITY; sc[i] = v; mx = fmaxf(mx, v); }
;                 mx = fmaxf(mx, __shfl_xor(mx, 32));
;                 const float m_new = fmaxf(m_run, mx);
;                 const float msafe = (m_new == -INFINITY) ? 0.f : m_new;
;                 const float alpha = __builtin_amdgcn_exp2f(m_run - msafe);
;                 const bool resc = __ballot(m_new > m_run) != 0ull;
;                 float ls = 0.f;
; #pragma unroll
;                 for (int i = 0; i < 16; ++i) { const float e = __builtin_amdgcn_exp2f(sc[i] - msafe); sc[i] = e; ls += e; }
;                 ls += __shfl_xor(ls, 32);
;                 l_run = l_run * alpha + ls; m_run = m_new;
;                 if (resc) {
; #pragma unroll
;                     for (int d = 0; d < 4; ++d)
; #pragma unroll
;                         for (int i = 0; i < 16; ++i) o[d][i] *= alpha;
;                 }
.LdsaA_s1_keep:
	v_cmp_neq_f32_e32 vcc, s78, v201
	s_nop 1
	v_cndmask_b32_e32 v86, 0, v201, vcc
	v_sub_f32_e32 v90, v86, v200
	v_pk_add_f32 v[236:237], v[236:237], v[90:91] op_sel_hi:[1,0] neg_lo:[0,1] neg_hi:[0,1]
	v_pk_add_f32 v[238:239], v[238:239], v[90:91] op_sel_hi:[1,0] neg_lo:[0,1] neg_hi:[0,1]
	v_pk_add_f32 v[240:241], v[240:241], v[90:91] op_sel_hi:[1,0] neg_lo:[0,1] neg_hi:[0,1]
	v_pk_add_f32 v[242:243], v[242:243], v[90:91] op_sel_hi:[1,0] neg_lo:[0,1] neg_hi:[0,1]
	v_pk_add_f32 v[244:245], v[244:245], v[90:91] op_sel_hi:[1,0] neg_lo:[0,1] neg_hi:[0,1]
	v_pk_add_f32 v[246:247], v[246:247], v[90:91] op_sel_hi:[1,0] neg_lo:[0,1] neg_hi:[0,1]
	v_pk_add_f32 v[248:249], v[248:249], v[90:91] op_sel_hi:[1,0] neg_lo:[0,1] neg_hi:[0,1]
	v_pk_add_f32 v[250:251], v[250:251], v[90:91] op_sel_hi:[1,0] neg_lo:[0,1] neg_hi:[0,1]
	v_exp_f32_e32 v236, v236
	v_exp_f32_e32 v237, v237
	v_exp_f32_e32 v238, v238
	v_exp_f32_e32 v239, v239
	v_exp_f32_e32 v240, v240
	v_exp_f32_e32 v241, v241
	v_exp_f32_e32 v242, v242
	v_exp_f32_e32 v243, v243
	v_exp_f32_e32 v244, v244
	v_exp_f32_e32 v245, v245
	v_exp_f32_e32 v246, v246
	v_exp_f32_e32 v247, v247
	v_exp_f32_e32 v248, v248
	v_exp_f32_e32 v249, v249
	v_exp_f32_e32 v250, v250
	v_exp_f32_e32 v251, v251
	v_pk_add_f32 v[92:93], v[236:237], v[238:239]
	v_pk_add_f32 v[92:93], v[92:93], v[240:241]
	v_pk_add_f32 v[92:93], v[92:93], v[242:243]
	v_pk_add_f32 v[92:93], v[92:93], v[244:245]
	v_pk_add_f32 v[92:93], v[92:93], v[246:247]
	v_pk_add_f32 v[92:93], v[92:93], v[248:249]
	v_pk_add_f32 v[92:93], v[92:93], v[250:251]
	s_nop 0
	v_add_f32_e32 v92, v92, v93
	ds_bpermute_b32 v215, v185, v92
	v_cvt_pk_f16_f32 v232, v236, v237
	v_cvt_pk_f16_f32 v233, v238, v239
	v_cvt_pk_f16_f32 v234, v240, v241
	v_cvt_pk_f16_f32 v235, v242, v243
	v_cvt_pk_f16_f32 v228, v244, v245
	v_cvt_pk_f16_f32 v229, v246, v247
	v_cvt_pk_f16_f32 v230, v248, v249
	v_cvt_pk_f16_f32 v231, v250, v251
	s_waitcnt lgkmcnt(0)
	v_add_f32_e32 v92, v92, v215
	v_add_f32_e32 v198, v198, v92
	ds_read_b128 v[236:239], v199 offset:34912
	ds_read_b128 v[240:243], v199 offset:39488
	ds_read_b128 v[244:247], v199 offset:44064
	ds_read_b128 v[248:251], v199 offset:48640
	ds_read_b128 v[80:83], v199 offset:34880
	ds_read_b128 v[84:87], v199 offset:39520
	ds_read_b128 v[88:91], v199 offset:44032
	ds_read_b128 v[92:95], v199 offset:48672
	s_waitcnt lgkmcnt(4)
	v_mfma_f32_32x32x16_f16 v[64:79], v[236:239], v[228:231], v[64:79]
	v_mfma_f32_32x32x16_f16 v[48:63], v[240:243], v[228:231], v[48:63]
	v_mfma_f32_32x32x16_f16 v[32:47], v[244:247], v[228:231], v[32:47]
	v_mfma_f32_32x32x16_f16 v[16:31], v[248:251], v[228:231], v[16:31]
	s_waitcnt lgkmcnt(0)
	v_mfma_f32_32x32x16_f16 v[64:79], v[80:83], v[232:235], v[64:79]
	v_mfma_f32_32x32x16_f16 v[48:63], v[84:87], v[232:235], v[48:63]
	v_mfma_f32_32x32x16_f16 v[32:47], v[88:91], v[232:235], v[32:47]
	v_mfma_f32_32x32x16_f16 v[16:31], v[92:95], v[232:235], v[16:31]

; __device__ __forceinline__ void diff_attn_item(CParams& p, int j, int layer, LAS unsigned char* lds, int b, int h, int qb, int tid_in, int lane_in, int wave) {
;     ...
;         mx = fmaxf(mx, __shfl_xor(mx, 32));
;         const float m_new = fmaxf(m_run, mx);
;         const float alpha = __builtin_amdgcn_exp2f(m_run - m_new);
;         const bool resc = __ballot(m_new > m_run) != 0ull;
;         float ls = 0.f;
; #pragma unroll
;         for (int sub = 0; sub < 2; ++sub)
; #pragma unroll
;             for (int i = 0; i < 16; ++i) { const float e = __builtin_amdgcn_exp2f(sc[sub][i] - m_new); sc[sub][i] = e; ls += e; }
;         ls += __shfl_xor(ls, 32);
;         l_run = l_run * alpha + ls; m_run = m_new;
;         if (resc) {
; #pragma unroll
;             for (int d = 0; d < 4; ++d)
; #pragma unroll
;                 for (int i = 0; i < 16; ++i) o[d][i] *= alpha;
;         }
.LdiffA_max:
	v_max3_f32 v249, v162, v163, v164
	v_max3_f32 v249, v249, v165, v166
	v_max3_f32 v249, v249, v167, v168
	v_max3_f32 v249, v249, v169, v170
	v_max3_f32 v249, v249, v171, v172
	v_max3_f32 v249, v249, v173, v174
	v_max3_f32 v249, v249, v175, v176
	v_max3_f32 v249, v249, v177, v228
	v_max3_f32 v249, v249, v229, v230
	v_max3_f32 v249, v249, v231, v232
	v_max3_f32 v249, v249, v233, v234
	v_max3_f32 v249, v249, v235, v236
	v_max3_f32 v249, v249, v237, v238
	v_max3_f32 v249, v249, v239, v240
	v_max3_f32 v249, v249, v241, v242
	v_max_f32_e32 v249, v249, v243
	s_waitcnt lgkmcnt(0)
	v_add_f32_e32 v249, v249, v213
	ds_bpermute_b32 v251, v185, v249
	s_waitcnt lgkmcnt(0)
	v_max3_f32 v248, v201, v249, v251
	v_add_f32_e32 v247, 0x41000000, v201
	v_cmp_gt_f32_e32 vcc, v248, v247
	s_cbranch_vccz .LdiffA_keep
	v_sub_f32_e32 v244, v201, v248
	v_exp_f32_e32 v244, v244
	v_mov_b32_e32 v201, v248
	s_nop 0
	v_mul_f32_e32 v197, v197, v244
	v_pk_mul_f32 v[50:51], v[50:51], v[244:245] op_sel_hi:[1,0]
	v_pk_mul_f32 v[52:53], v[52:53], v[244:245] op_sel_hi:[1,0]
	v_pk_mul_f32 v[54:55], v[54:55], v[244:245] op_sel_hi:[1,0]
	v_pk_mul_f32 v[56:57], v[56:57], v[244:245] op_sel_hi:[1,0]
	v_pk_mul_f32 v[58:59], v[58:59], v[244:245] op_sel_hi:[1,0]
	v_pk_mul_f32 v[60:61], v[60:61], v[244:245] op_sel_hi:[1,0]
	v_pk_mul_f32 v[62:63], v[62:63], v[244:245] op_sel_hi:[1,0]
	v_pk_mul_f32 v[64:65], v[64:65], v[244:245] op_sel_hi:[1,0]
	v_pk_mul_f32 v[34:35], v[34:35], v[244:245] op_sel_hi:[1,0]
	v_pk_mul_f32 v[36:37], v[36:37], v[244:245] op_sel_hi:[1,0]
	v_pk_mul_f32 v[38:39], v[38:39], v[244:245] op_sel_hi:[1,0]
	v_pk_mul_f32 v[40:41], v[40:41], v[244:245] op_sel_hi:[1,0]
	v_pk_mul_f32 v[42:43], v[42:43], v[244:245] op_sel_hi:[1,0]
	v_pk_mul_f32 v[44:45], v[44:45], v[244:245] op_sel_hi:[1,0]
	v_pk_mul_f32 v[46:47], v[46:47], v[244:245] op_sel_hi:[1,0]
	v_pk_mul_f32 v[48:49], v[48:49], v[244:245] op_sel_hi:[1,0]
	v_pk_mul_f32 v[18:19], v[18:19], v[244:245] op_sel_hi:[1,0]
	v_pk_mul_f32 v[20:21], v[20:21], v[244:245] op_sel_hi:[1,0]
	v_pk_mul_f32 v[22:23], v[22:23], v[244:245] op_sel_hi:[1,0]
	v_pk_mul_f32 v[24:25], v[24:25], v[244:245] op_sel_hi:[1,0]
	v_pk_mul_f32 v[26:27], v[26:27], v[244:245] op_sel_hi:[1,0]
	v_pk_mul_f32 v[28:29], v[28:29], v[244:245] op_sel_hi:[1,0]
	v_pk_mul_f32 v[30:31], v[30:31], v[244:245] op_sel_hi:[1,0]
	v_pk_mul_f32 v[32:33], v[32:33], v[244:245] op_sel_hi:[1,0]
	v_pk_mul_f32 v[2:3], v[2:3], v[244:245] op_sel_hi:[1,0]
	v_pk_mul_f32 v[4:5], v[4:5], v[244:245] op_sel_hi:[1,0]
	v_pk_mul_f32 v[6:7], v[6:7], v[244:245] op_sel_hi:[1,0]
	v_pk_mul_f32 v[8:9], v[8:9], v[244:245] op_sel_hi:[1,0]
	v_pk_mul_f32 v[10:11], v[10:11], v[244:245] op_sel_hi:[1,0]
	v_pk_mul_f32 v[12:13], v[12:13], v[244:245] op_sel_hi:[1,0]
	v_pk_mul_f32 v[14:15], v[14:15], v[244:245] op_sel_hi:[1,0]
	v_pk_mul_f32 v[16:17], v[16:17], v[244:245] op_sel_hi:[1,0]
; #define LAS __attribute__((address_space(3)))
; __device__ __forceinline__ f32x16 mma32(const h16x8 a, const h16x8 b, const f32x16 c) { return __builtin_amdgcn_mfma_f32_32x32x16_f16(a, b, c, 0, 0, 0); }
; __device__ __forceinline__ void diff_attn_item(CParams& p, int j, int layer, LAS unsigned char* lds, int b, int h, int qb, int tid_in, int lane_in, int wave) {
;     ...
;         mx = fmaxf(mx, __shfl_xor(mx, 32));
;         const float m_new = fmaxf(m_run, mx);
;         const float alpha = __builtin_amdgcn_exp2f(m_run - m_new);
;         const bool resc = __ballot(m_new > m_run) != 0ull;
;         float ls = 0.f;
; #pragma unroll
;         for (int sub = 0; sub < 2; ++sub)
; #pragma unroll
;             for (int i = 0; i < 16; ++i) { const float e = __builtin_amdgcn_exp2f(sc[sub][i] - m_new); sc[sub][i] = e; ls += e; }
;         ls += __shfl_xor(ls, 32);
;         l_run = l_run * alpha + ls; m_run = m_new;
;         if (resc) {
; #pragma unroll
;             for (int d = 0; d < 4; ++d)
; #pragma unroll
;                 for (int i = 0; i < 16; ++i) o[d][i] *= alpha;
;         }
; #pragma unroll
;         for (int sub = 0; sub < 2; ++sub)
; #pragma unroll
;             for (int s2 = 0; s2 < 2; ++s2) {
;                 h16x8 pf;
; #pragma unroll
;                 for (int jj = 0; jj < 8; ++jj) pf[jj] = (h16)sc[sub][8 * s2 + jj];
; #pragma unroll
;                 for (int d = 0; d < 4; ++d) {
;                     const int coff = 32 * d * 72 + ((((sub << 1) | s2) ^ d) << 4);
;                     const h16x4 lo = *(const LAS h16x4*)(Vt + vlo + coff), hi = *(const LAS h16x4*)(Vt + vhi + coff);
;                     h16x8 vf; vf[0] = lo[0]; vf[1] = lo[1]; vf[2] = lo[2]; vf[3] = lo[3]; vf[4] = hi[0]; vf[5] = hi[1]; vf[6] = hi[2]; vf[7] = hi[3];
;                     o[d] = mma32(vf, pf, o[d]);
;                 }
;             }
.LdiffA_keep:
	v_sub_f32_e32 v246, v201, v213
	v_pk_add_f32 v[162:163], v[162:163], v[246:247] op_sel_hi:[1,0] neg_lo:[0,1] neg_hi:[0,1]
	v_pk_add_f32 v[164:165], v[164:165], v[246:247] op_sel_hi:[1,0] neg_lo:[0,1] neg_hi:[0,1]
	v_pk_add_f32 v[166:167], v[166:167], v[246:247] op_sel_hi:[1,0] neg_lo:[0,1] neg_hi:[0,1]
	v_pk_add_f32 v[168:169], v[168:169], v[246:247] op_sel_hi:[1,0] neg_lo:[0,1] neg_hi:[0,1]
	v_pk_add_f32 v[170:171], v[170:171], v[246:247] op_sel_hi:[1,0] neg_lo:[0,1] neg_hi:[0,1]
	v_pk_add_f32 v[172:173], v[172:173], v[246:247] op_sel_hi:[1,0] neg_lo:[0,1] neg_hi:[0,1]
	v_pk_add_f32 v[174:175], v[174:175], v[246:247] op_sel_hi:[1,0] neg_lo:[0,1] neg_hi:[0,1]
	v_pk_add_f32 v[176:177], v[176:177], v[246:247] op_sel_hi:[1,0] neg_lo:[0,1] neg_hi:[0,1]
	v_pk_add_f32 v[228:229], v[228:229], v[246:247] op_sel_hi:[1,0] neg_lo:[0,1] neg_hi:[0,1]
	v_pk_add_f32 v[230:231], v[230:231], v[246:247] op_sel_hi:[1,0] neg_lo:[0,1] neg_hi:[0,1]
	v_pk_add_f32 v[232:233], v[232:233], v[246:247] op_sel_hi:[1,0] neg_lo:[0,1] neg_hi:[0,1]
	v_pk_add_f32 v[234:235], v[234:235], v[246:247] op_sel_hi:[1,0] neg_lo:[0,1] neg_hi:[0,1]
	v_pk_add_f32 v[236:237], v[236:237], v[246:247] op_sel_hi:[1,0] neg_lo:[0,1] neg_hi:[0,1]
	v_pk_add_f32 v[238:239], v[238:239], v[246:247] op_sel_hi:[1,0] neg_lo:[0,1] neg_hi:[0,1]
	v_pk_add_f32 v[240:241], v[240:241], v[246:247] op_sel_hi:[1,0] neg_lo:[0,1] neg_hi:[0,1]
	v_pk_add_f32 v[242:243], v[242:243], v[246:247] op_sel_hi:[1,0] neg_lo:[0,1] neg_hi:[0,1]
	v_exp_f32_e32 v162, v162
	v_exp_f32_e32 v163, v163
	v_exp_f32_e32 v164, v164
	v_exp_f32_e32 v165, v165
	v_exp_f32_e32 v166, v166
	v_exp_f32_e32 v167, v167
	v_exp_f32_e32 v168, v168
	v_exp_f32_e32 v169, v169
	v_exp_f32_e32 v170, v170
	v_exp_f32_e32 v171, v171
	v_exp_f32_e32 v172, v172
	v_exp_f32_e32 v173, v173
	v_exp_f32_e32 v174, v174
	v_exp_f32_e32 v175, v175
	v_exp_f32_e32 v176, v176
	v_exp_f32_e32 v177, v177
	v_exp_f32_e32 v228, v228
	v_exp_f32_e32 v229, v229
	v_exp_f32_e32 v230, v230
	v_exp_f32_e32 v231, v231
	v_exp_f32_e32 v232, v232
	v_exp_f32_e32 v233, v233
	v_exp_f32_e32 v234, v234
	v_exp_f32_e32 v235, v235
	v_exp_f32_e32 v236, v236
	v_exp_f32_e32 v237, v237
	v_exp_f32_e32 v238, v238
	v_exp_f32_e32 v239, v239
	v_exp_f32_e32 v240, v240
	v_exp_f32_e32 v241, v241
	v_exp_f32_e32 v242, v242
	v_exp_f32_e32 v243, v243
	v_pk_add_f32 v[250:251], v[162:163], v[164:165]
	v_pk_add_f32 v[250:251], v[250:251], v[166:167]
	v_pk_add_f32 v[250:251], v[250:251], v[168:169]
	v_pk_add_f32 v[250:251], v[250:251], v[170:171]
	v_pk_add_f32 v[250:251], v[250:251], v[172:173]
	v_pk_add_f32 v[250:251], v[250:251], v[174:175]
	v_pk_add_f32 v[250:251], v[250:251], v[176:177]
	v_pk_add_f32 v[250:251], v[250:251], v[228:229]
	v_pk_add_f32 v[250:251], v[250:251], v[230:231]
	v_pk_add_f32 v[250:251], v[250:251], v[232:233]
	v_pk_add_f32 v[250:251], v[250:251], v[234:235]
	v_pk_add_f32 v[250:251], v[250:251], v[236:237]
	v_pk_add_f32 v[250:251], v[250:251], v[238:239]
	v_pk_add_f32 v[250:251], v[250:251], v[240:241]
	v_pk_add_f32 v[250:251], v[250:251], v[242:243]
	s_nop 0
	v_add_f32_e32 v250, v250, v251
	ds_bpermute_b32 v251, v185, v250
	v_cvt_pk_f16_f32 v144, v162, v163
	v_cvt_pk_f16_f32 v145, v164, v165
	v_cvt_pk_f16_f32 v146, v166, v167
	v_cvt_pk_f16_f32 v147, v168, v169
	v_cvt_pk_f16_f32 v148, v170, v171
	v_cvt_pk_f16_f32 v149, v172, v173
	v_cvt_pk_f16_f32 v150, v174, v175
	v_cvt_pk_f16_f32 v151, v176, v177
	v_cvt_pk_f16_f32 v152, v228, v229
	v_cvt_pk_f16_f32 v153, v230, v231
	v_cvt_pk_f16_f32 v154, v232, v233
	v_cvt_pk_f16_f32 v155, v234, v235
	v_cvt_pk_f16_f32 v178, v236, v237
	v_cvt_pk_f16_f32 v179, v238, v239
	v_cvt_pk_f16_f32 v180, v240, v241
	v_cvt_pk_f16_f32 v181, v242, v243
	s_waitcnt lgkmcnt(0)
	v_add_f32_e32 v250, v250, v251
	v_add_f32_e32 v197, v197, v250
	ds_read_b128 v[66:69], v215 offset:34816
	ds_read_b128 v[70:73], v215 offset:39456
	ds_read_b128 v[74:77], v215 offset:44096
	ds_read_b128 v[78:81], v215 offset:48736
	ds_read_b128 v[82:85], v215 offset:34848
	ds_read_b128 v[86:89], v215 offset:39424
	ds_read_b128 v[90:93], v215 offset:44128
	ds_read_b128 v[94:97], v215 offset:48704
	s_waitcnt lgkmcnt(4)
	v_mfma_f32_32x32x16_f16 v[50:65], v[66:69], v[144:147], v[50:65]
	v_mfma_f32_32x32x16_f16 v[34:49], v[70:73], v[144:147], v[34:49]
	v_mfma_f32_32x32x16_f16 v[18:33], v[74:77], v[144:147], v[18:33]
	v_mfma_f32_32x32x16_f16 v[2:17], v[78:81], v[144:147], v[2:17]
	ds_read_b128 v[66:69], v215 offset:34880
	ds_read_b128 v[70:73], v215 offset:39520
	ds_read_b128 v[74:77], v215 offset:44032
	ds_read_b128 v[78:81], v215 offset:48672
	s_waitcnt lgkmcnt(4)
	v_mfma_f32_32x32x16_f16 v[50:65], v[82:85], v[148:151], v[50:65]
	v_mfma_f32_32x32x16_f16 v[34:49], v[86:89], v[148:151], v[34:49]
	v_mfma_f32_32x32x16_f16 v[18:33], v[90:93], v[148:151], v[18:33]
	v_mfma_f32_32x32x16_f16 v[2:17], v[94:97], v[148:151], v[2:17]
	ds_read_b128 v[82:85], v215 offset:34912
	ds_read_b128 v[86:89], v215 offset:39488
	ds_read_b128 v[90:93], v215 offset:44064
	ds_read_b128 v[94:97], v215 offset:48640
	s_waitcnt lgkmcnt(4)
	v_mfma_f32_32x32x16_f16 v[50:65], v[66:69], v[152:155], v[50:65]
	v_mfma_f32_32x32x16_f16 v[34:49], v[70:73], v[152:155], v[34:49]
	v_mfma_f32_32x32x16_f16 v[18:33], v[74:77], v[152:155], v[18:33]
	v_mfma_f32_32x32x16_f16 v[2:17], v[78:81], v[152:155], v[2:17]
	s_waitcnt lgkmcnt(0)
	v_mfma_f32_32x32x16_f16 v[50:65], v[82:85], v[178:181], v[50:65]
	v_mfma_f32_32x32x16_f16 v[34:49], v[86:89], v[178:181], v[34:49]
	v_mfma_f32_32x32x16_f16 v[18:33], v[90:93], v[178:181], v[18:33]
	v_mfma_f32_32x32x16_f16 v[2:17], v[94:97], v[178:181], v[2:17]
